# speedup vs baseline: 1.0233x; 1.0104x over previous
;   __device__ __forceinline__ const float* in(int i) const { return reinterpret_cast<const float*>(ld64(i * 8)); }
;   __device__ __forceinline__ unsigned char* ws() const { return reinterpret_cast<unsigned char*>(ld64(27 * 8)); }
; __device__ __forceinline__ void phase_convert(const PRef& p) {
;   unsigned char* ws = p.ws();
;   constexpr int U0 = 704, U1 = U0 + 352, U2 = U1 + 704, U3 = U2 + 352, U4 = U3 + 384, U5 = U4 + 128;
;   for (int u = blockIdx.x; u < U5; u += gridDim.x) {
;     if (u < U0)      convert_weight(p.in(7), p.in(8), true, 1024, DFF, 5632, (bf16*)(ws + WS_W1A), u);
;     else if (u < U1) convert_weight(p.in(9), nullptr, false, DFF, 1024, 1024, (bf16*)(ws + WS_WD1), u - U0);
;     else if (u < U2) convert_weight(p.in(21), p.in(22), true, 1024, DFF, 5632, (bf16*)(ws + WS_W1B), u - U1);
;     else if (u < U3) convert_weight(p.in(23), nullptr, false, DFF, 1024, 1024, (bf16*)(ws + WS_WD2), u - U2);
;     else if (u < U4) convert_weight(p.in(12), nullptr, false, 1024, 3072, 3072, (bf16*)(ws + WS_WIN), u - U3);
;     else             convert_weight(p.in(18), nullptr, false, 1024, 1024, 1024, (bf16*)(ws + WS_WOUT), u - U4);
;   }
.LBB0_1138:
	v_readlane_b32 s0, v254, 10
	v_readlane_b32 s1, v254, 0
	s_mov_b32 s16, -1
	s_mov_b32 s17, 0
	s_mov_b32 s101, 0
	s_cmp_eq_u32 s0, 1
	s_cselect_b32 s16, 0x96, s16
	s_cselect_b32 s17, 0x2c0, s17
	s_cselect_b32 s101, 0x580, s101
	s_cmp_eq_u32 s0, 6
	s_cselect_b32 s16, 0x10, s16
	s_cselect_b32 s17, 0x580, s17
	s_cselect_b32 s101, 0x6e0, s101
	s_cmp_eq_u32 s0, 8
	s_cselect_b32 s16, 0x96, s16
	s_cselect_b32 s17, 0x6e0, s17
	s_cselect_b32 s101, 0x840, s101
	s_cmp_eq_u32 s0, 2
	s_cselect_b32 s16, 0x2c, s16
	s_cselect_b32 s17, 0x840, s17
	s_cselect_b32 s101, 0x9c0, s101
	s_cmp_eq_u32 s0, 4
	s_cselect_b32 s16, 0x30, s16
	s_cselect_b32 s17, 0x9c0, s17
	s_cselect_b32 s101, 0xa40, s101
	s_cmp_lt_u32 s1, s16
	s_cbranch_scc1 .Lmy_cv_return
	v_readlane_b32 s100, v254, 1
	s_sub_i32 s100, s100, s16
	s_sub_i32 s18, s1, s16
	s_add_i32 s18, s18, s17
	s_cmp_ge_i32 s18, s101
	s_cbranch_scc1 .Lmy_cv_return
	s_lshl_b32 s17, s18, 8
	s_or_b32 s17, s17, 15
	s_lshl_b32 s16, s18, 3
	s_add_i32 s16, s16, 0x7be00
	v_mov_b32_e32 v2, 0x23fd8
	ds_read_b64 v[2:3], v2
	s_waitcnt lgkmcnt(0)
	v_readfirstlane_b32 s4, v2
	v_readfirstlane_b32 s5, v3
	s_branch .Lmy_cv_entry

;   __device__ __forceinline__ const float* in(int i) const { return reinterpret_cast<const float*>(ld64(i * 8)); }
;   __device__ __forceinline__ unsigned char* ws() const { return reinterpret_cast<unsigned char*>(ld64(27 * 8)); }
; __device__ __forceinline__ void phase_convert(const PRef& p) {
;   unsigned char* ws = p.ws();
;   constexpr int U0 = 704, U1 = U0 + 352, U2 = U1 + 704, U3 = U2 + 352, U4 = U3 + 384, U5 = U4 + 128;
;   for (int u = blockIdx.x; u < U5; u += gridDim.x) {
;     if (u < U0)      convert_weight(p.in(7), p.in(8), true, 1024, DFF, 5632, (bf16*)(ws + WS_W1A), u);
;     else if (u < U1) convert_weight(p.in(9), nullptr, false, DFF, 1024, 1024, (bf16*)(ws + WS_WD1), u - U0);
;     else if (u < U2) convert_weight(p.in(21), p.in(22), true, 1024, DFF, 5632, (bf16*)(ws + WS_W1B), u - U1);
;     else if (u < U3) convert_weight(p.in(23), nullptr, false, DFF, 1024, 1024, (bf16*)(ws + WS_WD2), u - U2);
;     else if (u < U4) convert_weight(p.in(12), nullptr, false, 1024, 3072, 3072, (bf16*)(ws + WS_WIN), u - U3);
;     else             convert_weight(p.in(18), nullptr, false, 1024, 1024, 1024, (bf16*)(ws + WS_WOUT), u - U4);
;   }
.LBB0_1143:
	s_or_b64 exec, exec, s[0:1]
	s_movk_i32 s101, 0x2c0
	s_mov_b64 s[0:1], src_shared_base
	v_readlane_b32 s0, v254, 5
	s_cmp_lg_u32 s0, -1
	s_cselect_b32 s0, s0, 0
	v_mov_b32_e32 v2, s0
	v_readlane_b32 s0, v254, 6
	s_cselect_b32 s4, s1, 0
	s_cmp_lg_u32 s0, -1
	v_mov_b32_e32 v3, s4
	s_cselect_b32 s0, s0, 0
	s_cselect_b32 s1, s1, 0
	flat_load_dword v0, v[2:3] sc0 sc1
	s_waitcnt vmcnt(0)
	v_mov_b32_e32 v2, s0
	v_mov_b32_e32 v3, s1
	flat_load_dword v2, v[2:3] sc0 sc1
	s_waitcnt vmcnt(0)
	v_readlane_b32 s0, v254, 19
	v_readlane_b32 s1, v254, 20
	s_andn2_b64 vcc, exec, s[0:1]
	s_waitcnt lgkmcnt(0)
	v_readfirstlane_b32 s4, v0
	v_readfirstlane_b32 s5, v2
	s_cbranch_vccnz .LBB0_1166
	v_readlane_b32 s100, v254, 1
	v_readlane_b32 s16, v254, 43
	v_readlane_b32 s17, v254, 41
	v_readlane_b32 s18, v254, 0
